# attention: waves 4-7 delayed by s_sleep 10 at each chunk start so MFMA and softmax VALU phases of SIMD partners overlap
# baseline (speedup 1.0000x reference)
.LBB0_815:
	v_readfirstlane_b32 s24, v160
	s_nop 3
	s_cmpk_lt_u32 s24, 0x100
	s_cbranch_scc1 .Latt_nostag
	s_sleep 10
